# speedup vs baseline: 1.0197x; 1.0026x over previous
; #define SLOAD(i, k0) do { sr_[i].vs0 = *reinterpret_cast<const bf16x8*>(&Vh[(size_t)((k0) + sr) * LDQ + sc]); sr_[i].vs1 = *reinterpret_cast<const bf16x8*>(&Vh[(size_t)((k0) + 32 + sr) * LDQ + sc]); \
;     sr_[i].ks0 = *reinterpret_cast<const bf16x8*>(&Kh[(size_t)((k0) + sr) * LDQ + sc]); sr_[i].ks1 = *reinterpret_cast<const bf16x8*>(&Kh[(size_t)((k0) + 32 + sr) * LDQ + sc]); } while (0)
; #define SWRITE(b, i) do { *(bf16x8*)((char*)V_lds + (b) * SHM_V + vst0) = sr_[i].vs0;          \
;     *(bf16x8*)((char*)V_lds + (b) * SHM_V + vst1) = sr_[i].vs1; int kc = sc * 2;               \
;     *(bf16x8*)((char*)K_lds + (b) * SHM_K + KSWZ(sr, kc)) = sr_[i].ks0;                       \
;     *(bf16x8*)((char*)K_lds + (b) * SHM_K + KSWZ(32 + sr, kc)) = sr_[i].ks1; } while (0)
; template <bool SAFE>
; __device__ __forceinline__ void diff_core(const bf16* __restrict__ Kh, const bf16* __restrict__ Vh, const int NT, const bf16x8* qr, char* lds,
;                                           const int wid, const int lane_unused, f32x16* o, f32x16& lacc, float& l_reg) {
;     ...
;   const int kw0 = KSWZ(sr, sc * 2), kw1 = KSWZ(32 + sr, sc * 2);
;   SLOAD(0, 0); asm volatile("s_waitcnt vmcnt(0)" ::: "memory"); SWRITE(0, 0);
;   SLOAD(0, 64); asm volatile("s_waitcnt vmcnt(0)" ::: "memory"); SWRITE(1, 0); __syncthreads();
;   SLOAD(0, 128);
;   FIXUP(K_lds, true);
;   int bc = 1, bp = 0, bn = 2;
.LBB0_104:
	s_or_b64 exec, exec, s[4:5]
	v_and_b32_e32 v200, 63, v0
	v_lshlrev_b32_e32 v0, 4, v2
	v_and_b32_e32 v0, 0xc0, v0
	v_and_or_b32 v0, v1, 24, v0
	v_and_b32_e32 v2, 32, v4
	v_and_b32_e32 v1, 0x100, v1
	s_waitcnt lgkmcnt(0)
	v_add_u32_e32 v9, s62, v3
	v_or3_b32 v8, v0, v2, v1
	ds_read_b128 v[0:3], v9 offset:192
	ds_read_b128 v[4:7], v9 offset:224
	ds_read_b128 v[50:53], v9 offset:128
	ds_read_b128 v[54:57], v9 offset:160
	v_sub_f32_e32 v16, v16, v48
	v_sub_f32_e32 v17, v17, v48
	v_sub_f32_e32 v18, v18, v48
	v_sub_f32_e32 v19, v19, v48
	v_sub_f32_e32 v20, v20, v48
	v_sub_f32_e32 v21, v21, v48
	v_sub_f32_e32 v22, v22, v48
	v_sub_f32_e32 v23, v23, v48
	v_sub_f32_e32 v24, v24, v48
	v_sub_f32_e32 v25, v25, v48
	v_sub_f32_e32 v26, v26, v48
	v_sub_f32_e32 v27, v27, v48
	v_sub_f32_e32 v28, v28, v48
	v_sub_f32_e32 v29, v29, v48
	v_sub_f32_e32 v30, v30, v48
	v_sub_f32_e32 v31, v31, v48
	v_sub_f32_e32 v32, v32, v48
	v_sub_f32_e32 v33, v33, v48
	v_sub_f32_e32 v34, v34, v48
	v_sub_f32_e32 v35, v35, v48
	v_sub_f32_e32 v36, v36, v48
	v_sub_f32_e32 v37, v37, v48
	v_sub_f32_e32 v38, v38, v48
	v_sub_f32_e32 v39, v39, v48
	v_sub_f32_e32 v40, v40, v48
	v_sub_f32_e32 v41, v41, v48
	v_sub_f32_e32 v42, v42, v48
	v_sub_f32_e32 v43, v43, v48
	v_sub_f32_e32 v44, v44, v48
	v_sub_f32_e32 v45, v45, v48
	v_sub_f32_e32 v46, v46, v48
	v_sub_f32_e32 v47, v47, v48
	v_exp_f32_e32 v16, v16
	v_exp_f32_e32 v17, v17
	v_exp_f32_e32 v18, v18
	v_exp_f32_e32 v19, v19
	v_exp_f32_e32 v20, v20
	v_exp_f32_e32 v21, v21
	v_exp_f32_e32 v22, v22
	v_exp_f32_e32 v23, v23
	v_exp_f32_e32 v24, v24
	v_exp_f32_e32 v25, v25
	v_exp_f32_e32 v26, v26
	v_exp_f32_e32 v27, v27
	v_exp_f32_e32 v28, v28
	v_exp_f32_e32 v29, v29
	v_exp_f32_e32 v30, v30
	v_exp_f32_e32 v31, v31
	v_exp_f32_e32 v32, v32
	v_exp_f32_e32 v33, v33
	v_exp_f32_e32 v34, v34
	v_exp_f32_e32 v35, v35
	v_exp_f32_e32 v36, v36
	v_exp_f32_e32 v37, v37
	v_exp_f32_e32 v38, v38
	v_exp_f32_e32 v39, v39
	v_exp_f32_e32 v40, v40
	v_exp_f32_e32 v41, v41
	v_exp_f32_e32 v42, v42
	v_exp_f32_e32 v43, v43
	v_exp_f32_e32 v44, v44
	v_exp_f32_e32 v45, v45
	v_exp_f32_e32 v46, v46
	v_exp_f32_e32 v47, v47
	s_lshl_b32 s12, s8, 7
	s_cmp_lg_u32 0, -1
	s_cselect_b32 s5, 0, 0
	s_waitcnt lgkmcnt(2)
	v_pk_mul_f32 v[14:15], v[6:7], 0 op_sel_hi:[1,0]
	v_xor_b32_e32 v80, 0x80000000, v48
	v_add_u32_e32 v211, s5, v8
	v_pk_mul_f32 v[10:11], v[2:3], 0 op_sel_hi:[1,0]
	s_waitcnt lgkmcnt(0)
	v_pk_mul_f32 v[6:7], v[56:57], 0 op_sel_hi:[1,0]
	v_pk_mul_f32 v[2:3], v[52:53], 0 op_sel_hi:[1,0]
	v_pk_mul_f32 v[12:13], v[4:5], 0 op_sel_hi:[1,0]
	v_pk_mul_f32 v[8:9], v[0:1], 0 op_sel_hi:[1,0]
	v_pk_mul_f32 v[4:5], v[54:55], 0 op_sel_hi:[1,0]
	v_pk_mul_f32 v[0:1], v[50:51], 0 op_sel_hi:[1,0]
	v_cvt_pk_bf16_f32 v160, v16, v17
	v_cvt_pk_bf16_f32 v161, v18, v19
	v_cvt_pk_bf16_f32 v182, v20, v21
	v_cvt_pk_bf16_f32 v183, v22, v23
	v_cvt_pk_bf16_f32 v170, v24, v25
	v_cvt_pk_bf16_f32 v171, v26, v27
	v_cvt_pk_bf16_f32 v186, v28, v29
	v_cvt_pk_bf16_f32 v187, v30, v31
	v_cvt_pk_bf16_f32 v180, v32, v33
	v_cvt_pk_bf16_f32 v181, v34, v35
	v_cvt_pk_bf16_f32 v178, v36, v37
	v_cvt_pk_bf16_f32 v179, v38, v39
	v_cvt_pk_bf16_f32 v188, v40, v41
	v_cvt_pk_bf16_f32 v189, v42, v43
	v_cvt_pk_bf16_f32 v174, v44, v45
	v_cvt_pk_bf16_f32 v175, v46, v47
	v_mov_b32_e32 v64, 0
	v_mov_b64_e32 v[46:47], v[14:15]
	v_mov_b64_e32 v[62:63], v[14:15]
	v_mov_b64_e32 v[30:31], v[14:15]
	v_mov_b32_e32 v81, v80
	v_mov_b32_e32 v82, v80
	v_mov_b32_e32 v83, v80
	v_mov_b32_e32 v84, v80
	v_mov_b32_e32 v85, v80
	v_mov_b32_e32 v86, v80
	v_mov_b32_e32 v87, v80
	v_mov_b32_e32 v88, v80
	v_mov_b32_e32 v89, v80
	v_mov_b32_e32 v90, v80
	v_mov_b32_e32 v91, v80
	v_mov_b32_e32 v92, v80
	v_mov_b32_e32 v93, v80
	v_mov_b32_e32 v94, v80
	v_mov_b32_e32 v95, v80
	s_mov_b32 s4, 0
	s_mov_b32 s5, 1
	v_lshl_add_u64 v[190:191], s[10:11], 0, v[194:195]
	v_mad_u32_u24 v247, v201, s80, v194
	s_add_i32 s93, s92, -1
	s_mov_b32 s9, 2
	v_mov_b64_e32 v[44:45], v[12:13]
	v_mov_b64_e32 v[42:43], v[10:11]
	v_mov_b64_e32 v[40:41], v[8:9]
	v_mov_b64_e32 v[38:39], v[6:7]
	v_mov_b64_e32 v[36:37], v[4:5]
	v_mov_b64_e32 v[34:35], v[2:3]
	v_mov_b64_e32 v[32:33], v[0:1]
	v_mov_b64_e32 v[60:61], v[12:13]
	v_mov_b64_e32 v[58:59], v[10:11]
	v_mov_b64_e32 v[56:57], v[8:9]
	v_mov_b64_e32 v[54:55], v[6:7]
	v_mov_b64_e32 v[52:53], v[4:5]
	v_mov_b64_e32 v[50:51], v[2:3]
	v_mov_b64_e32 v[48:49], v[0:1]
	v_mov_b64_e32 v[28:29], v[12:13]
	v_mov_b64_e32 v[26:27], v[10:11]
	v_mov_b64_e32 v[24:25], v[8:9]
	v_mov_b64_e32 v[22:23], v[6:7]
	v_mov_b64_e32 v[20:21], v[4:5]
	v_mov_b64_e32 v[18:19], v[2:3]
	v_mov_b64_e32 v[16:17], v[0:1]
	s_mov_b32 s6, 1
	v_mov_b32_e32 v65, v64
	v_mov_b32_e32 v66, v64
	v_mov_b32_e32 v67, v64
	v_mov_b32_e32 v68, v64
	v_mov_b32_e32 v69, v64
	v_mov_b32_e32 v70, v64
	v_mov_b32_e32 v71, v64
	v_mov_b32_e32 v72, v64
	v_mov_b32_e32 v73, v64
	v_mov_b32_e32 v74, v64
	v_mov_b32_e32 v75, v64
	v_mov_b32_e32 v76, v64
	v_mov_b32_e32 v77, v64
	v_mov_b32_e32 v78, v64
	v_mov_b32_e32 v79, v64
	s_lshl_b32 s98, s6, 14
	v_add_u32_e32 v76, s98, v207
	v_add_u32_e32 v77, s98, v208
	ds_read_b128 v[68:71], v76 offset:49152
	ds_read_b128 v[72:75], v76 offset:57344
	s_waitcnt lgkmcnt(0)
	v_mov_b32_e32 v176, v180
	v_mov_b32_e32 v177, v181
	v_mov_b32_e32 v180, v160
	v_mov_b32_e32 v181, v161
	v_mov_b32_e32 v184, v170
	v_mov_b32_e32 v185, v171
	v_mov_b32_e32 v172, v188
	v_mov_b32_e32 v173, v189
; template <int KS, bool SAFE> __device__ __forceinline__ void fused_ks(f32x16* o, f32x16& lacc, int vb, const VFrag& cur, VFrag& nxt, f32x16& p0, f32x16& p1, float& ps, ...
;   if constexpr (KS < 3) { vfrag_issue<KS + 1>(nxt, vb); asm volatile("s_waitcnt lgkmcnt(8)" ::: "memory"); }
;   else asm volatile("s_waitcnt lgkmcnt(0)" ::: "memory");
;   const bf16x8 pa = (KS == 0) ? pa0 : (KS == 1) ? pa1 : (KS == 2) ? pa2 : pa3;
;   SBAR();
;   o[0] = MFMA32(pa, PKV(cur.l0, cur.h0), o[0]); SBAR(); sm1_chunk<KS * 4 + 0>(p0, p1); if constexpr (KS > 0) SM2_UNIT(2 * KS - 1); SBAR();
;   o[1] = MFMA32(pa, PKV(cur.l1, cur.h1), o[1]); SBAR(); sm1_chunk<KS * 4 + 1>(p0, p1);
;   if (dow) {
;     if constexpr (KS == 0) { asm volatile("s_waitcnt vmcnt(0)" ::: "memory"); *reinterpret_cast<bf16x8*>(sd.k0) = st.ks0; }
;     else if constexpr (KS == 1) *reinterpret_cast<bf16x8*>(sd.k1) = st.ks1;
;     else if constexpr (KS == 2) *reinterpret_cast<bf16x8*>(sd.v0) = st.vs0;
;     else *reinterpret_cast<bf16x8*>(sd.v1) = st.vs1;
;   }
;   SBAR();
;   o[2] = MFMA32(pa, PKV(cur.l2, cur.h2), o[2]); SBAR(); sm1_chunk<KS * 4 + 2>(p0, p1); SM2_UNIT(2 * KS); SBAR();
;   o[3] = MFMA32(pa, PKV(cur.l3, cur.h3), o[3]); SBAR(); sm1_chunk<KS * 4 + 3>(p0, p1); SBAR();
;   if constexpr (!SAFE) { lacc = MFMA32(pa, ones, lacc); SBAR(); }
; }
; template <bool SAFE> ...
;   bf16x8 kb[8];
; #pragma unroll
;   for (int d0 = 0; d0 < 4; ++d0) { const int cb = (cb0 + d0 * 16 + hi * 8) * 2;
;     kb[2 * d0] = *reinterpret_cast<const bf16x8*>((const char*)Ks + KSWZ(r32, cb));
;     kb[2 * d0 + 1] = *reinterpret_cast<const bf16x8*>((const char*)Ks + KSWZ(32 + r32, cb)); }
;   VFrag fa, fb;
;   vfrag_issue<0>(fa, vb);
;   p0 = MFMA32(kb[0], qr[0], cinit); p1 = MFMA32(kb[1], qr[0], cinit);
; #pragma unroll
;   for (int d0 = 1; d0 < 4; ++d0) { p0 = MFMA32(kb[2 * d0], qr[d0], p0); p1 = MFMA32(kb[2 * d0 + 1], qr[d0], p1); }
;   SBAR();
;   unsigned a0, a1, b0, b1; ps = 0.f;
;   fused_ks<0, SAFE>(o, lacc, vb, fa, fb, p0, p1, ps, a0, a1, b0, b1, pa0, pa1, pa2, pa3, st, sd, dow, ones);
;   fused_ks<1, SAFE>(o, lacc, vb, fb, fa, p0, p1, ps, a0, a1, b0, b1, pa0, pa1, pa2, pa3, st, sd, dow, ones);
;   fused_ks<2, SAFE>(o, lacc, vb, fa, fb, p0, p1, ps, a0, a1, b0, b1, pa0, pa1, pa2, pa3, st, sd, dow, ones);
;   fused_ks<3, SAFE>(o, lacc, vb, fb, fa, p0, p1, ps, a0, a1, b0, b1, pa0, pa1, pa2, pa3, st, sd, dow, ones);
.LBB0_105:
	ds_read_b128 v[212:215], v77 offset:49152
	ds_read_b128 v[216:219], v77 offset:57344
	s_lshl_b32 s7, s6, 14
	s_add_i32 s66, s7, 0
	s_add_i32 s98, s5, 2
	s_min_i32 s98, s98, s93
	s_mul_i32 s98, s98, 0x60000
	s_add_u32 s98, s10, s98
	s_addc_u32 s99, s11, 0
	s_add_u32 s100, s98, 0x30000
	s_addc_u32 s101, s99, 0
	v_add_u32_e32 v78, s66, v209
	v_mfma_f32_32x32x16_bf16 v[112:127], v[68:71], v[132:135], v[80:95]
	v_add_u32_e32 v160, s66, v210
	v_lshl_add_u32 v194, s4, 14, v211
	s_mov_b32 s8, s9
	s_lshl_b32 s9, s9, 14
	s_add_i32 s9, s9, 0
	v_add_u32_e32 v76, s9, v207
	v_mfma_f32_32x32x16_bf16 v[96:111], v[72:75], v[132:135], v[80:95]
	ds_read_b128 v[68:71], v78 offset:49152
	ds_read_b128 v[72:75], v78 offset:57344
	v_add_u32_e32 v188, s9, v205
	v_add_u32_e32 v161, s9, v203
	v_add_u32_e32 v170, s9, v204
	v_mfma_f32_16x16x32_bf16 v[64:67], v[180:183], v[148:151], v[64:67]
	s_waitcnt lgkmcnt(3)
	v_mfma_f32_32x32x16_bf16 v[112:127], v[212:215], v[136:139], v[112:127]
	ds_read_b128 v[212:215], v160 offset:49152
	s_waitcnt vmcnt(3)
	ds_write_b128 v161, v[166:169] offset:49152
	global_load_dwordx4 v[166:169], v247, s[98:99] offset:1024
	s_waitcnt lgkmcnt(4)
	v_mfma_f32_32x32x16_bf16 v[96:111], v[216:219], v[136:139], v[96:111]
	ds_read_b128 v[216:219], v160 offset:57344
	v_add_u32_e32 v189, s9, v206
	v_add_u32_e32 v77, s9, v208
	v_mfma_f32_16x16x32_bf16 v[64:67], v[184:187], v[148:151], v[64:67]
	s_waitcnt lgkmcnt(4)
	v_mfma_f32_32x32x16_bf16 v[112:127], v[68:71], v[140:143], v[112:127]
	ds_read_b64_tr_b16 v[220:221], v194 offset:0
	ds_read_b64_tr_b16 v[222:223], v194 offset:0x800
	s_waitcnt vmcnt(3)
	ds_write_b128 v170, v[162:165] offset:49152
	global_load_dwordx4 v[162:165], v247, s[100:101] offset:1024
	v_mfma_f32_16x16x32_bf16 v[64:67], v[176:179], v[148:151], v[64:67]
	s_waitcnt lgkmcnt(6)
	v_mfma_f32_32x32x16_bf16 v[96:111], v[72:75], v[140:143], v[96:111]
	v_mfma_f32_16x16x32_bf16 v[64:67], v[172:175], v[148:151], v[64:67]
	s_waitcnt lgkmcnt(5)
	v_mfma_f32_32x32x16_bf16 v[112:127], v[212:215], v[144:147], v[112:127]
	ds_read_b64_tr_b16 v[212:213], v194 offset:0x200
	ds_read_b64_tr_b16 v[214:215], v194 offset:0xa00
	ds_read_b64_tr_b16 v[224:225], v194 offset:0x400
	ds_read_b64_tr_b16 v[226:227], v194 offset:0xc00
	ds_read_b64_tr_b16 v[228:229], v194 offset:0x600
	ds_read_b64_tr_b16 v[230:231], v194 offset:0xe00
	s_waitcnt lgkmcnt(7)
	v_mfma_f32_32x32x16_bf16 v[96:111], v[216:219], v[144:147], v[96:111]
	ds_read_b64_tr_b16 v[216:217], v194 offset:0x1000
	ds_read_b64_tr_b16 v[218:219], v194 offset:0x1800
	ds_read_b64_tr_b16 v[232:233], v194 offset:0x1200
	ds_read_b64_tr_b16 v[234:235], v194 offset:0x1a00
	ds_read_b64_tr_b16 v[236:237], v194 offset:0x1400
	ds_read_b64_tr_b16 v[238:239], v194 offset:0x1c00
	ds_read_b64_tr_b16 v[240:241], v194 offset:0x1600
	ds_read_b64_tr_b16 v[242:243], v194 offset:0x1e00
	s_waitcnt lgkmcnt(8)
	v_mfma_f32_32x32x16_bf16 v[48:63], v[180:183], v[220:223], v[48:63]
	s_nop 0
	v_exp_f32_e32 v112, v112
	v_exp_f32_e32 v113, v113
	v_mfma_f32_32x32x16_bf16 v[32:47], v[180:183], v[212:215], v[32:47]
	v_exp_f32_e32 v114, v114
	v_exp_f32_e32 v115, v115
	v_mfma_f32_32x32x16_bf16 v[0:15], v[180:183], v[224:227], v[0:15]
	v_exp_f32_e32 v171, v116
	v_exp_f32_e32 v220, v117
	v_mfma_f32_32x32x16_bf16 v[16:31], v[180:183], v[228:231], v[16:31]
	v_exp_f32_e32 v221, v118
	v_exp_f32_e32 v222, v119
	v_cvt_pk_bf16_f32 v180, v112, v113
	v_cvt_pk_bf16_f32 v181, v114, v115
	ds_read_b64_tr_b16 v[112:113], v194 offset:0x2000
	ds_read_b64_tr_b16 v[114:115], v194 offset:0x2800
	ds_read_b64_tr_b16 v[116:117], v194 offset:0x2200
	ds_read_b64_tr_b16 v[118:119], v194 offset:0x2a00
	ds_read_b64_tr_b16 v[248:249], v194 offset:0x2400
	ds_read_b64_tr_b16 v[250:251], v194 offset:0x2c00
	ds_read_b64_tr_b16 v[212:213], v194 offset:0x2600
	ds_read_b64_tr_b16 v[214:215], v194 offset:0x2e00
	s_waitcnt lgkmcnt(8)
	v_mfma_f32_32x32x16_bf16 v[48:63], v[184:187], v[216:219], v[48:63]
	v_cvt_pk_bf16_f32 v182, v171, v220
	v_cvt_pk_bf16_f32 v183, v221, v222
	v_exp_f32_e32 v120, v120
	v_exp_f32_e32 v121, v121
	v_mfma_f32_32x32x16_bf16 v[32:47], v[184:187], v[232:235], v[32:47]
	v_exp_f32_e32 v122, v122
	v_exp_f32_e32 v123, v123
	v_mfma_f32_32x32x16_bf16 v[0:15], v[184:187], v[236:239], v[0:15]
	v_exp_f32_e32 v160, v124
	v_exp_f32_e32 v161, v125
	v_mfma_f32_32x32x16_bf16 v[16:31], v[184:187], v[240:243], v[16:31]
	v_exp_f32_e32 v220, v126
	v_exp_f32_e32 v221, v127
	v_cvt_pk_bf16_f32 v184, v120, v121
	v_cvt_pk_bf16_f32 v185, v122, v123
	s_waitcnt lgkmcnt(0)
	s_barrier
	v_mfma_f32_32x32x16_bf16 v[48:63], v[176:179], v[112:115], v[48:63]
	ds_read_b128 v[68:71], v76 offset:49152
	ds_read_b128 v[72:75], v76 offset:57344
	ds_read_b64_tr_b16 v[120:121], v194 offset:0x3000
	ds_read_b64_tr_b16 v[122:123], v194 offset:0x3800
	ds_read_b64_tr_b16 v[124:125], v194 offset:0x3200
	ds_read_b64_tr_b16 v[126:127], v194 offset:0x3a00
	ds_read_b64_tr_b16 v[252:253], v194 offset:0x3400
	ds_read_b64_tr_b16 v[254:255], v194 offset:0x3c00
	ds_read_b64_tr_b16 v[216:217], v194 offset:0x3600
	ds_read_b64_tr_b16 v[218:219], v194 offset:0x3e00
	v_cvt_pk_bf16_f32 v186, v160, v161
	v_cvt_pk_bf16_f32 v187, v220, v221
	v_exp_f32_e32 v96, v96
	v_exp_f32_e32 v97, v97
	v_mfma_f32_32x32x16_bf16 v[32:47], v[176:179], v[116:119], v[32:47]
	v_exp_f32_e32 v98, v98
	v_exp_f32_e32 v99, v99
	s_waitcnt vmcnt(3)
	ds_write_b128 v188, v[156:159]
	global_load_dwordx4 v[156:159], v247, s[98:99] offset:2048
	v_mfma_f32_32x32x16_bf16 v[0:15], v[176:179], v[248:251], v[0:15]
	v_exp_f32_e32 v100, v100
	v_exp_f32_e32 v101, v101
	v_mfma_f32_32x32x16_bf16 v[16:31], v[176:179], v[212:215], v[16:31]
	v_cvt_pk_bf16_f32 v176, v96, v97
	v_cvt_pk_bf16_f32 v177, v98, v99
	v_exp_f32_e32 v96, v102
	v_exp_f32_e32 v97, v103
	s_waitcnt lgkmcnt(0)
	v_mfma_f32_32x32x16_bf16 v[48:63], v[172:175], v[120:123], v[48:63]
	v_cvt_pk_bf16_f32 v178, v100, v101
	v_cvt_pk_bf16_f32 v179, v96, v97
	v_exp_f32_e32 v98, v104
	v_exp_f32_e32 v99, v105
	v_mfma_f32_32x32x16_bf16 v[32:47], v[172:175], v[124:127], v[32:47]
	v_exp_f32_e32 v96, v106
	v_exp_f32_e32 v97, v107
	s_waitcnt vmcnt(3)
	ds_write_b128 v189, v[152:155]
	global_load_dwordx4 v[152:155], v247, s[100:101] offset:2048
	v_mfma_f32_32x32x16_bf16 v[0:15], v[172:175], v[252:255], v[0:15]
	v_exp_f32_e32 v100, v108
	v_exp_f32_e32 v101, v109
	v_mfma_f32_32x32x16_bf16 v[16:31], v[172:175], v[216:219], v[16:31]
	v_cvt_pk_bf16_f32 v172, v98, v99
	v_cvt_pk_bf16_f32 v173, v96, v97
	v_exp_f32_e32 v102, v110
	v_exp_f32_e32 v103, v111
	v_cvt_pk_bf16_f32 v174, v100, v101
	v_cvt_pk_bf16_f32 v175, v102, v103
	s_add_i32 s5, s5, 1
	s_mov_b32 s9, s4
	s_mov_b32 s4, s6
	s_cmp_lg_u32 s92, s5
	s_mov_b32 s6, s8
	s_cbranch_scc1 .LBB0_105
; #define MFMA32(a, b, c) __builtin_amdgcn_mfma_f32_32x32x16_bf16(a, b, c, 0, 0, 0)
; template <bool SAFE>
; __device__ __forceinline__ void diff_core(const bf16* __restrict__ Kh, const bf16* __restrict__ Vh, const int NT, const bf16x8* qr, char* lds,
;                                           const int wid, const int lane_unused, f32x16* o, f32x16& lacc, float& l_reg) {
;     ...
;   pv_d0(o, vb0 + bp * SHM_V, pa0, pa1, pa2, pa3);
;   if constexpr (!SAFE) {
;     lacc = MFMA32(pa0, ones, lacc); lacc = MFMA32(pa1, ones, lacc); lacc = MFMA32(pa2, ones, lacc); lacc = MFMA32(pa3, ones, lacc); }
; __device__ __forceinline__ void diff_attn_item(const bf16* __restrict__ qkv, bf16* __restrict__ mix, const float* __restrict__ dg,
;                                int tok0  , int key0  , int seq, int head, float lam, float oscale, const int W) {
;     ...
;     bool bad = (FORCE_SAFE != 0);
; #pragma unroll
;     for (int r = 0; r < 16; ++r) bad = bad || !(lacc[r] < 1.0e30f);
;     if (lane == 0) flag_l[wid] = __any(bad) ? 1 : 0;
	v_mov_b32_e32 v160, v180
	v_mov_b32_e32 v161, v181
	v_mov_b32_e32 v170, v184
	v_mov_b32_e32 v171, v185
	v_mov_b32_e32 v180, v176
	v_mov_b32_e32 v181, v177
	v_mov_b32_e32 v188, v172
	v_mov_b32_e32 v189, v173
	s_waitcnt vmcnt(0)
	v_add_u32_e32 v168, s7, v211
	ds_read_b64_tr_b16 v[80:81], v168 offset:0
	ds_read_b64_tr_b16 v[82:83], v168 offset:0x800
	ds_read_b64_tr_b16 v[84:85], v168 offset:0x1000
	ds_read_b64_tr_b16 v[86:87], v168 offset:0x1800
	ds_read_b64_tr_b16 v[88:89], v168 offset:0x2000
	ds_read_b64_tr_b16 v[90:91], v168 offset:0x2800
	ds_read_b64_tr_b16 v[92:93], v168 offset:0x3000
	ds_read_b64_tr_b16 v[94:95], v168 offset:0x3800
	s_waitcnt lgkmcnt(0)
	s_waitcnt vmcnt(0)
	v_mov_b32_e32 v162, v182
	v_mov_b32_e32 v163, v183
	v_mov_b32_e32 v172, v186
	v_mov_b32_e32 v173, v187
	v_mov_b32_e32 v182, v178
	v_mov_b32_e32 v183, v179
	v_mov_b32_e32 v190, v174
	v_mov_b32_e32 v191, v175
	ds_read_b64_tr_b16 v[96:97], v168 offset:0x200
	ds_read_b64_tr_b16 v[98:99], v168 offset:0xa00
	ds_read_b64_tr_b16 v[100:101], v168 offset:0x1200
	ds_read_b64_tr_b16 v[102:103], v168 offset:0x1a00
	ds_read_b64_tr_b16 v[104:105], v168 offset:0x2200
	ds_read_b64_tr_b16 v[106:107], v168 offset:0x2a00
	ds_read_b64_tr_b16 v[108:109], v168 offset:0x3200
	ds_read_b64_tr_b16 v[110:111], v168 offset:0x3a00
	s_waitcnt lgkmcnt(0)
	ds_read_b64_tr_b16 v[112:113], v168 offset:0x400
	ds_read_b64_tr_b16 v[114:115], v168 offset:0xc00
	ds_read_b64_tr_b16 v[116:117], v168 offset:0x1400
	ds_read_b64_tr_b16 v[118:119], v168 offset:0x1c00
	ds_read_b64_tr_b16 v[120:121], v168 offset:0x2400
	ds_read_b64_tr_b16 v[122:123], v168 offset:0x2c00
	ds_read_b64_tr_b16 v[124:125], v168 offset:0x3400
	ds_read_b64_tr_b16 v[126:127], v168 offset:0x3c00
	s_waitcnt lgkmcnt(0)
	ds_read_b64_tr_b16 v[152:153], v168 offset:0x600
	ds_read_b64_tr_b16 v[154:155], v168 offset:0xe00
	ds_read_b64_tr_b16 v[156:157], v168 offset:0x1600
	ds_read_b64_tr_b16 v[158:159], v168 offset:0x1e00
	ds_read_b64_tr_b16 v[164:165], v168 offset:0x2600
	ds_read_b64_tr_b16 v[166:167], v168 offset:0x2e00
	ds_read_b64_tr_b16 v[174:175], v168 offset:0x3600
	ds_read_b64_tr_b16 v[176:177], v168 offset:0x3e00
	s_waitcnt lgkmcnt(0)
	v_mfma_f32_16x16x32_bf16 v[64:67], v[160:163], v[148:151], v[64:67]
	v_cmp_eq_u32_e32 vcc, 0, v200
	v_mfma_f32_32x32x16_bf16 v[48:63], v[160:163], v[80:83], v[48:63]
	v_mfma_f32_32x32x16_bf16 v[32:47], v[160:163], v[96:99], v[32:47]
	v_mfma_f32_32x32x16_bf16 v[0:15], v[160:163], v[112:115], v[0:15]
	v_mfma_f32_32x32x16_bf16 v[16:31], v[160:163], v[152:155], v[16:31]
	v_mfma_f32_16x16x32_bf16 v[64:67], v[170:173], v[148:151], v[64:67]
	v_mfma_f32_32x32x16_bf16 v[48:63], v[170:173], v[84:87], v[48:63]
	v_mfma_f32_32x32x16_bf16 v[32:47], v[170:173], v[100:103], v[32:47]
	v_mfma_f32_32x32x16_bf16 v[0:15], v[170:173], v[116:119], v[0:15]
	v_mfma_f32_32x32x16_bf16 v[16:31], v[170:173], v[156:159], v[16:31]
	v_mfma_f32_16x16x32_bf16 v[64:67], v[180:183], v[148:151], v[64:67]
	v_mfma_f32_32x32x16_bf16 v[48:63], v[180:183], v[88:91], v[48:63]
	v_mfma_f32_32x32x16_bf16 v[32:47], v[180:183], v[104:107], v[32:47]
	v_mfma_f32_32x32x16_bf16 v[0:15], v[180:183], v[120:123], v[0:15]
	v_mfma_f32_32x32x16_bf16 v[16:31], v[180:183], v[164:167], v[16:31]
	v_mfma_f32_16x16x32_bf16 v[64:67], v[188:191], v[148:151], v[64:67]
	v_mfma_f32_32x32x16_bf16 v[48:63], v[188:191], v[92:95], v[48:63]
	v_mfma_f32_32x32x16_bf16 v[32:47], v[188:191], v[108:111], v[32:47]
	v_mfma_f32_32x32x16_bf16 v[0:15], v[188:191], v[124:127], v[0:15]
	v_mfma_f32_32x32x16_bf16 v[16:31], v[188:191], v[174:177], v[16:31]
	v_and_b32_e32 v248, 15, v200
	v_lshrrev_b32_e32 v249, 4, v200
	v_and_b32_e32 v250, 1, v200
	v_lshlrev_b32_e32 v249, 4, v249
	v_lshl_add_u32 v249, v250, 6, v249
	v_add_u32_e32 v249, s62, v249
	v_cmp_gt_u32_e64 s[98:99], 2, v248
	v_lshl_add_u32 v250, v198, 4, s62
	s_nop 7
	s_and_saveexec_b64 s[100:101], s[98:99]
	ds_write_b128 v249, v[64:67]
	s_mov_b64 exec, s[100:101]
	s_waitcnt lgkmcnt(0)
	ds_read_b128 v[64:67], v250
	ds_read_b128 v[68:71], v250 offset:32
	ds_read_b128 v[72:75], v250 offset:64
	ds_read_b128 v[76:79], v250 offset:96
	s_waitcnt lgkmcnt(0)
	s_and_saveexec_b64 s[6:7], vcc
	s_cbranch_execz .LBB0_108
	s_nop 5
	v_cmp_ngt_f32_e32 vcc, s85, v64
	v_cmp_ngt_f32_e64 s[4:5], s85, v65
	s_or_b64 s[4:5], vcc, s[4:5]
	v_cmp_ngt_f32_e32 vcc, s85, v66
	s_or_b64 s[4:5], s[4:5], vcc
	v_cmp_ngt_f32_e32 vcc, s85, v67
	s_or_b64 s[4:5], s[4:5], vcc
	v_cmp_ngt_f32_e32 vcc, s85, v68
	s_or_b64 s[4:5], s[4:5], vcc
	v_cmp_ngt_f32_e32 vcc, s85, v69
	s_or_b64 s[4:5], s[4:5], vcc
	v_cmp_ngt_f32_e32 vcc, s85, v70
	s_or_b64 s[4:5], s[4:5], vcc
	v_cmp_ngt_f32_e32 vcc, s85, v71
	s_or_b64 s[4:5], s[4:5], vcc
	v_cmp_ngt_f32_e32 vcc, s85, v72
	s_or_b64 s[4:5], s[4:5], vcc
	v_cmp_ngt_f32_e32 vcc, s85, v73
	s_or_b64 s[4:5], s[4:5], vcc
	v_cmp_ngt_f32_e32 vcc, s85, v74
	s_or_b64 s[4:5], s[4:5], vcc
	v_cmp_ngt_f32_e32 vcc, s85, v75
	s_or_b64 s[4:5], s[4:5], vcc
	v_cmp_ngt_f32_e32 vcc, s85, v76
	s_or_b64 s[4:5], s[4:5], vcc
	v_cmp_ngt_f32_e32 vcc, s85, v77
	s_or_b64 s[4:5], s[4:5], vcc
	v_cmp_ngt_f32_e32 vcc, s85, v78
	s_or_b64 s[4:5], s[4:5], vcc
	v_cmp_ngt_f32_e32 vcc, s85, v79
	s_or_b64 s[4:5], s[4:5], vcc
	v_cndmask_b32_e64 v80, 0, 1, s[4:5]
	v_cmp_ne_u32_e32 vcc, 0, v80
	s_cmp_lg_u64 vcc, 0
	s_cselect_b64 s[4:5], -1, 0
	v_cndmask_b32_e64 v80, 0, 1, s[4:5]
	v_readlane_b32 s4, v246, 17
	s_nop 1
	v_mov_b32_e32 v81, s4
	ds_write_b32 v81, v80

; #define SLOAD(i, k0) do { sr_[i].vs0 = *reinterpret_cast<const bf16x8*>(&Vh[(size_t)((k0) + sr) * LDQ + sc]); sr_[i].vs1 = *reinterpret_cast<const bf16x8*>(&Vh[(size_t)((k0) + 32 + sr) * LDQ + sc]); \
;     sr_[i].ks0 = *reinterpret_cast<const bf16x8*>(&Kh[(size_t)((k0) + sr) * LDQ + sc]); sr_[i].ks1 = *reinterpret_cast<const bf16x8*>(&Kh[(size_t)((k0) + 32 + sr) * LDQ + sc]); } while (0)
; #define SWRITE(b, i) do { *(bf16x8*)((char*)V_lds + (b) * SHM_V + vst0) = sr_[i].vs0;          \
;     *(bf16x8*)((char*)V_lds + (b) * SHM_V + vst1) = sr_[i].vs1; int kc = sc * 2;               \
;     *(bf16x8*)((char*)K_lds + (b) * SHM_K + KSWZ(sr, kc)) = sr_[i].ks0;                       \
;     *(bf16x8*)((char*)K_lds + (b) * SHM_K + KSWZ(32 + sr, kc)) = sr_[i].ks1; } while (0)
; template <bool SAFE>
; __device__ __forceinline__ void diff_core(const bf16* __restrict__ Kh, const bf16* __restrict__ Vh, const int NT, const bf16x8* qr, char* lds,
;                                           const int wid, const int lane_unused, f32x16* o, f32x16& lacc, float& l_reg) {
;     ...
;   const int kw0 = KSWZ(sr, sc * 2), kw1 = KSWZ(32 + sr, sc * 2);
;   SLOAD(0, 0); asm volatile("s_waitcnt vmcnt(0)" ::: "memory"); SWRITE(0, 0);
;   SLOAD(0, 64); asm volatile("s_waitcnt vmcnt(0)" ::: "memory"); SWRITE(1, 0); __syncthreads();
;   SLOAD(0, 128);
;   FIXUP(K_lds, true);
;   int bc = 1, bp = 0, bn = 2;
.LBB0_315:
	s_or_b64 exec, exec, s[6:7]
	v_and_b32_e32 v200, 63, v0
	v_lshlrev_b32_e32 v0, 4, v2
	v_and_b32_e32 v0, 0xc0, v0
	v_and_or_b32 v0, v1, 24, v0
	v_and_b32_e32 v2, 32, v4
	v_and_b32_e32 v1, 0x100, v1
	s_waitcnt lgkmcnt(0)
	v_add_u32_e32 v9, s62, v3
	v_or3_b32 v8, v0, v2, v1
	ds_read_b128 v[0:3], v9 offset:192
	ds_read_b128 v[4:7], v9 offset:224
	ds_read_b128 v[50:53], v9 offset:128
	ds_read_b128 v[54:57], v9 offset:160
	v_sub_f32_e32 v16, v16, v48
	v_sub_f32_e32 v17, v17, v48
	v_sub_f32_e32 v18, v18, v48
	v_sub_f32_e32 v19, v19, v48
	v_sub_f32_e32 v20, v20, v48
	v_sub_f32_e32 v21, v21, v48
	v_sub_f32_e32 v22, v22, v48
	v_sub_f32_e32 v23, v23, v48
	v_sub_f32_e32 v24, v24, v48
	v_sub_f32_e32 v25, v25, v48
	v_sub_f32_e32 v26, v26, v48
	v_sub_f32_e32 v27, v27, v48
	v_sub_f32_e32 v28, v28, v48
	v_sub_f32_e32 v29, v29, v48
	v_sub_f32_e32 v30, v30, v48
	v_sub_f32_e32 v31, v31, v48
	v_sub_f32_e32 v32, v32, v48
	v_sub_f32_e32 v33, v33, v48
	v_sub_f32_e32 v34, v34, v48
	v_sub_f32_e32 v35, v35, v48
	v_sub_f32_e32 v36, v36, v48
	v_sub_f32_e32 v37, v37, v48
	v_sub_f32_e32 v38, v38, v48
	v_sub_f32_e32 v39, v39, v48
	v_sub_f32_e32 v40, v40, v48
	v_sub_f32_e32 v41, v41, v48
	v_sub_f32_e32 v42, v42, v48
	v_sub_f32_e32 v43, v43, v48
	v_sub_f32_e32 v44, v44, v48
	v_sub_f32_e32 v45, v45, v48
	v_sub_f32_e32 v46, v46, v48
	v_sub_f32_e32 v47, v47, v48
	v_exp_f32_e32 v16, v16
	v_exp_f32_e32 v17, v17
	v_exp_f32_e32 v18, v18
	v_exp_f32_e32 v19, v19
	v_exp_f32_e32 v20, v20
	v_exp_f32_e32 v21, v21
	v_exp_f32_e32 v22, v22
	v_exp_f32_e32 v23, v23
	v_exp_f32_e32 v24, v24
	v_exp_f32_e32 v25, v25
	v_exp_f32_e32 v26, v26
	v_exp_f32_e32 v27, v27
	v_exp_f32_e32 v28, v28
	v_exp_f32_e32 v29, v29
	v_exp_f32_e32 v30, v30
	v_exp_f32_e32 v31, v31
	v_exp_f32_e32 v32, v32
	v_exp_f32_e32 v33, v33
	v_exp_f32_e32 v34, v34
	v_exp_f32_e32 v35, v35
	v_exp_f32_e32 v36, v36
	v_exp_f32_e32 v37, v37
	v_exp_f32_e32 v38, v38
	v_exp_f32_e32 v39, v39
	v_exp_f32_e32 v40, v40
	v_exp_f32_e32 v41, v41
	v_exp_f32_e32 v42, v42
	v_exp_f32_e32 v43, v43
	v_exp_f32_e32 v44, v44
	v_exp_f32_e32 v45, v45
	v_exp_f32_e32 v46, v46
	v_exp_f32_e32 v47, v47
	s_lshl_b32 s20, s26, 7
	s_cmp_lg_u32 0, -1
	s_cselect_b32 s7, 0, 0
	s_waitcnt lgkmcnt(2)
	v_pk_mul_f32 v[14:15], v[6:7], 0 op_sel_hi:[1,0]
	v_xor_b32_e32 v80, 0x80000000, v48
	v_add_u32_e32 v211, s7, v8
	v_pk_mul_f32 v[10:11], v[2:3], 0 op_sel_hi:[1,0]
	s_waitcnt lgkmcnt(0)
	v_pk_mul_f32 v[6:7], v[56:57], 0 op_sel_hi:[1,0]
	v_pk_mul_f32 v[2:3], v[52:53], 0 op_sel_hi:[1,0]
	v_pk_mul_f32 v[12:13], v[4:5], 0 op_sel_hi:[1,0]
	v_pk_mul_f32 v[8:9], v[0:1], 0 op_sel_hi:[1,0]
	v_pk_mul_f32 v[4:5], v[54:55], 0 op_sel_hi:[1,0]
	v_pk_mul_f32 v[0:1], v[50:51], 0 op_sel_hi:[1,0]
	v_cvt_pk_bf16_f32 v160, v16, v17
	v_cvt_pk_bf16_f32 v161, v18, v19
	v_cvt_pk_bf16_f32 v182, v20, v21
	v_cvt_pk_bf16_f32 v183, v22, v23
	v_cvt_pk_bf16_f32 v170, v24, v25
	v_cvt_pk_bf16_f32 v171, v26, v27
	v_cvt_pk_bf16_f32 v186, v28, v29
	v_cvt_pk_bf16_f32 v187, v30, v31
	v_cvt_pk_bf16_f32 v180, v32, v33
	v_cvt_pk_bf16_f32 v181, v34, v35
	v_cvt_pk_bf16_f32 v178, v36, v37
	v_cvt_pk_bf16_f32 v179, v38, v39
	v_cvt_pk_bf16_f32 v188, v40, v41
	v_cvt_pk_bf16_f32 v189, v42, v43
	v_cvt_pk_bf16_f32 v174, v44, v45
	v_cvt_pk_bf16_f32 v175, v46, v47
	v_mov_b32_e32 v64, 0
	v_mov_b64_e32 v[46:47], v[14:15]
	v_mov_b64_e32 v[62:63], v[14:15]
	v_mov_b64_e32 v[30:31], v[14:15]
	v_mov_b32_e32 v81, v80
	v_mov_b32_e32 v82, v80
	v_mov_b32_e32 v83, v80
	v_mov_b32_e32 v84, v80
	v_mov_b32_e32 v85, v80
	v_mov_b32_e32 v86, v80
	v_mov_b32_e32 v87, v80
	v_mov_b32_e32 v88, v80
	v_mov_b32_e32 v89, v80
	v_mov_b32_e32 v90, v80
	v_mov_b32_e32 v91, v80
	v_mov_b32_e32 v92, v80
	v_mov_b32_e32 v93, v80
	v_mov_b32_e32 v94, v80
	v_mov_b32_e32 v95, v80
	s_mov_b32 s6, 0
	s_mov_b32 s7, 1
	v_lshl_add_u64 v[190:191], s[14:15], 0, v[194:195]
	v_mad_u32_u24 v247, v201, s41, v194
	s_add_i32 s64, s55, -1
	s_mov_b32 s27, 2
	v_mov_b64_e32 v[44:45], v[12:13]
	v_mov_b64_e32 v[42:43], v[10:11]
	v_mov_b64_e32 v[40:41], v[8:9]
	v_mov_b64_e32 v[38:39], v[6:7]
	v_mov_b64_e32 v[36:37], v[4:5]
	v_mov_b64_e32 v[34:35], v[2:3]
	v_mov_b64_e32 v[32:33], v[0:1]
	v_mov_b64_e32 v[60:61], v[12:13]
	v_mov_b64_e32 v[58:59], v[10:11]
	v_mov_b64_e32 v[56:57], v[8:9]
	v_mov_b64_e32 v[54:55], v[6:7]
	v_mov_b64_e32 v[52:53], v[4:5]
	v_mov_b64_e32 v[50:51], v[2:3]
	v_mov_b64_e32 v[48:49], v[0:1]
	v_mov_b64_e32 v[28:29], v[12:13]
	v_mov_b64_e32 v[26:27], v[10:11]
	v_mov_b64_e32 v[24:25], v[8:9]
	v_mov_b64_e32 v[22:23], v[6:7]
	v_mov_b64_e32 v[20:21], v[4:5]
	v_mov_b64_e32 v[18:19], v[2:3]
	v_mov_b64_e32 v[16:17], v[0:1]
	s_mov_b32 s10, 1
	v_mov_b32_e32 v65, v64
	v_mov_b32_e32 v66, v64
	v_mov_b32_e32 v67, v64
	v_mov_b32_e32 v68, v64
	v_mov_b32_e32 v69, v64
	v_mov_b32_e32 v70, v64
	v_mov_b32_e32 v71, v64
	v_mov_b32_e32 v72, v64
	v_mov_b32_e32 v73, v64
	v_mov_b32_e32 v74, v64
	v_mov_b32_e32 v75, v64
	v_mov_b32_e32 v76, v64
	v_mov_b32_e32 v77, v64
	v_mov_b32_e32 v78, v64
	v_mov_b32_e32 v79, v64
	s_lshl_b32 s98, s10, 14
	v_add_u32_e32 v76, s98, v207
	v_add_u32_e32 v77, s98, v208
	ds_read_b128 v[68:71], v76 offset:49152
	ds_read_b128 v[72:75], v76 offset:57344
	s_waitcnt lgkmcnt(0)
	v_mov_b32_e32 v176, v180
	v_mov_b32_e32 v177, v181
	v_mov_b32_e32 v180, v160
	v_mov_b32_e32 v181, v161
	v_mov_b32_e32 v184, v170
	v_mov_b32_e32 v185, v171
	v_mov_b32_e32 v172, v188
	v_mov_b32_e32 v173, v189
; #define SBAR() __builtin_amdgcn_sched_barrier(0)
; template <bool SAFE> ...
;   bf16x8 kb[8];
; #pragma unroll
;   for (int d0 = 0; d0 < 4; ++d0) { const int cb = (cb0 + d0 * 16 + hi * 8) * 2;
;     kb[2 * d0] = *reinterpret_cast<const bf16x8*>((const char*)Ks + KSWZ(r32, cb));
;     kb[2 * d0 + 1] = *reinterpret_cast<const bf16x8*>((const char*)Ks + KSWZ(32 + r32, cb)); }
;   VFrag fa, fb;
;   vfrag_issue<0>(fa, vb);
;   p0 = MFMA32(kb[0], qr[0], cinit); p1 = MFMA32(kb[1], qr[0], cinit);
; #pragma unroll
;   for (int d0 = 1; d0 < 4; ++d0) { p0 = MFMA32(kb[2 * d0], qr[d0], p0); p1 = MFMA32(kb[2 * d0 + 1], qr[d0], p1); }
;   SBAR();
;   unsigned a0, a1, b0, b1; ps = 0.f;
;   fused_ks<0, SAFE>(o, lacc, vb, fa, fb, p0, p1, ps, a0, a1, b0, b1, pa0, pa1, pa2, pa3, st, sd, dow, ones);
;   fused_ks<1, SAFE>(o, lacc, vb, fb, fa, p0, p1, ps, a0, a1, b0, b1, pa0, pa1, pa2, pa3, st, sd, dow, ones);
;   fused_ks<2, SAFE>(o, lacc, vb, fa, fb, p0, p1, ps, a0, a1, b0, b1, pa0, pa1, pa2, pa3, st, sd, dow, ones);
;   fused_ks<3, SAFE>(o, lacc, vb, fb, fa, p0, p1, ps, a0, a1, b0, b1, pa0, pa1, pa2, pa3, st, sd, dow, ones);
;   SM2_UNIT(7);
;   if constexpr (SAFE) { auto rr = __builtin_amdgcn_permlane32_swap(__float_as_uint(ps), __float_as_uint(ps), false, false);
;     ps = __uint_as_float(rr[0]) + __uint_as_float(rr[1]); }
;   SBAR();
; }
; template <bool SAFE>
; __device__ __forceinline__ void diff_core(const bf16* __restrict__ Kh, const bf16* __restrict__ Vh, const int NT, const bf16x8* qr, char* lds,
;                                           const int wid, const int lane_unused, f32x16* o, f32x16& lacc, float& l_reg) {
;     ...
;   for (int j = 1; j < NT; ++j) {
;     const bool dow = true;
;     const bf16* Kc = (const bf16*)((const char*)K_lds + bc * SHM_K);
;     StgDst sd;
;     sd.v0 = (char*)V_lds + bn * SHM_V + vst0; sd.v1 = (char*)V_lds + bn * SHM_V + vst1;
;     sd.k0 = (char*)K_lds + bn * SHM_K + kw0;  sd.k1 = (char*)K_lds + bn * SHM_K + kw1;
;     tile_step<SAFE>(o, lacc, Kc, vb0 + bp * SHM_V, qr, rk, hi, cb0, p0, p1, cinit, ps, pa0, pa1, pa2, pa3, sr_[0], sd, dow, ones);
;     SLOAD(0, min(j + 2, NT - 1) * 64);
;     SBAR();
;     if constexpr (SAFE) FIXUP(Kc, false);
;     asm volatile("s_waitcnt lgkmcnt(0)" ::: "memory"); __builtin_amdgcn_s_barrier(); asm volatile("" ::: "memory");
;     const int t_ = bp; bp = bc; bc = bn; bn = t_;
.LBB0_316:
	ds_read_b128 v[212:215], v77 offset:49152
	ds_read_b128 v[216:219], v77 offset:57344
	s_lshl_b32 s11, s10, 14
	s_add_i32 s8, s11, 0
	s_add_i32 s98, s7, 2
	s_min_i32 s98, s98, s64
	s_mul_i32 s98, s98, 0x60000
	s_add_u32 s98, s14, s98
	s_addc_u32 s99, s15, 0
	s_add_u32 s100, s98, 0x30000
	s_addc_u32 s101, s99, 0
	v_add_u32_e32 v78, s8, v209
	v_mfma_f32_32x32x16_bf16 v[112:127], v[68:71], v[132:135], v[80:95]
	v_add_u32_e32 v160, s8, v210
	v_lshl_add_u32 v194, s6, 14, v211
	s_lshl_b32 s9, s27, 14
	s_add_i32 s9, s9, 0
	s_mov_b32 s26, s27
	v_add_u32_e32 v76, s9, v207
	v_mfma_f32_32x32x16_bf16 v[96:111], v[72:75], v[132:135], v[80:95]
	ds_read_b128 v[68:71], v78 offset:49152
	ds_read_b128 v[72:75], v78 offset:57344
	v_add_u32_e32 v188, s9, v205
	v_add_u32_e32 v161, s9, v203
	v_add_u32_e32 v170, s9, v204
	v_mfma_f32_16x16x32_bf16 v[64:67], v[180:183], v[148:151], v[64:67]
	s_waitcnt lgkmcnt(3)
	v_mfma_f32_32x32x16_bf16 v[112:127], v[212:215], v[136:139], v[112:127]
	ds_read_b128 v[212:215], v160 offset:49152
	s_waitcnt vmcnt(3)
	ds_write_b128 v161, v[166:169] offset:49152
	global_load_dwordx4 v[166:169], v247, s[98:99] offset:1024
	s_waitcnt lgkmcnt(4)
	v_mfma_f32_32x32x16_bf16 v[96:111], v[216:219], v[136:139], v[96:111]
	ds_read_b128 v[216:219], v160 offset:57344
	v_add_u32_e32 v189, s9, v206
	v_add_u32_e32 v77, s9, v208
	v_mfma_f32_16x16x32_bf16 v[64:67], v[184:187], v[148:151], v[64:67]
	s_waitcnt lgkmcnt(4)
	v_mfma_f32_32x32x16_bf16 v[112:127], v[68:71], v[140:143], v[112:127]
	ds_read_b64_tr_b16 v[220:221], v194 offset:0
	ds_read_b64_tr_b16 v[222:223], v194 offset:0x800
	s_waitcnt vmcnt(3)
	ds_write_b128 v170, v[162:165] offset:49152
	global_load_dwordx4 v[162:165], v247, s[100:101] offset:1024
	v_mfma_f32_16x16x32_bf16 v[64:67], v[176:179], v[148:151], v[64:67]
	s_waitcnt lgkmcnt(6)
	v_mfma_f32_32x32x16_bf16 v[96:111], v[72:75], v[140:143], v[96:111]
	v_mfma_f32_16x16x32_bf16 v[64:67], v[172:175], v[148:151], v[64:67]
	s_waitcnt lgkmcnt(5)
	v_mfma_f32_32x32x16_bf16 v[112:127], v[212:215], v[144:147], v[112:127]
	ds_read_b64_tr_b16 v[212:213], v194 offset:0x200
	ds_read_b64_tr_b16 v[214:215], v194 offset:0xa00
	ds_read_b64_tr_b16 v[224:225], v194 offset:0x400
	ds_read_b64_tr_b16 v[226:227], v194 offset:0xc00
	ds_read_b64_tr_b16 v[228:229], v194 offset:0x600
	ds_read_b64_tr_b16 v[230:231], v194 offset:0xe00
	s_waitcnt lgkmcnt(7)
	v_mfma_f32_32x32x16_bf16 v[96:111], v[216:219], v[144:147], v[96:111]
	ds_read_b64_tr_b16 v[216:217], v194 offset:0x1000
	ds_read_b64_tr_b16 v[218:219], v194 offset:0x1800
	ds_read_b64_tr_b16 v[232:233], v194 offset:0x1200
	ds_read_b64_tr_b16 v[234:235], v194 offset:0x1a00
	ds_read_b64_tr_b16 v[236:237], v194 offset:0x1400
	ds_read_b64_tr_b16 v[238:239], v194 offset:0x1c00
	ds_read_b64_tr_b16 v[240:241], v194 offset:0x1600
	ds_read_b64_tr_b16 v[242:243], v194 offset:0x1e00
	s_waitcnt lgkmcnt(8)
	v_mfma_f32_32x32x16_bf16 v[48:63], v[180:183], v[220:223], v[48:63]
	s_nop 0
	v_exp_f32_e32 v112, v112
	v_exp_f32_e32 v113, v113
	v_mfma_f32_32x32x16_bf16 v[32:47], v[180:183], v[212:215], v[32:47]
	v_exp_f32_e32 v114, v114
	v_exp_f32_e32 v115, v115
	v_mfma_f32_32x32x16_bf16 v[0:15], v[180:183], v[224:227], v[0:15]
	v_exp_f32_e32 v171, v116
	v_exp_f32_e32 v220, v117
	v_mfma_f32_32x32x16_bf16 v[16:31], v[180:183], v[228:231], v[16:31]
	v_exp_f32_e32 v221, v118
	v_exp_f32_e32 v222, v119
	v_cvt_pk_bf16_f32 v180, v112, v113
	v_cvt_pk_bf16_f32 v181, v114, v115
	ds_read_b64_tr_b16 v[112:113], v194 offset:0x2000
	ds_read_b64_tr_b16 v[114:115], v194 offset:0x2800
	ds_read_b64_tr_b16 v[116:117], v194 offset:0x2200
	ds_read_b64_tr_b16 v[118:119], v194 offset:0x2a00
	ds_read_b64_tr_b16 v[248:249], v194 offset:0x2400
	ds_read_b64_tr_b16 v[250:251], v194 offset:0x2c00
	ds_read_b64_tr_b16 v[212:213], v194 offset:0x2600
	ds_read_b64_tr_b16 v[214:215], v194 offset:0x2e00
	s_waitcnt lgkmcnt(8)
	v_mfma_f32_32x32x16_bf16 v[48:63], v[184:187], v[216:219], v[48:63]
	v_cvt_pk_bf16_f32 v182, v171, v220
	v_cvt_pk_bf16_f32 v183, v221, v222
	v_exp_f32_e32 v120, v120
	v_exp_f32_e32 v121, v121
	v_mfma_f32_32x32x16_bf16 v[32:47], v[184:187], v[232:235], v[32:47]
	v_exp_f32_e32 v122, v122
	v_exp_f32_e32 v123, v123
	v_mfma_f32_32x32x16_bf16 v[0:15], v[184:187], v[236:239], v[0:15]
	v_exp_f32_e32 v160, v124
	v_exp_f32_e32 v161, v125
	v_mfma_f32_32x32x16_bf16 v[16:31], v[184:187], v[240:243], v[16:31]
	v_exp_f32_e32 v220, v126
	v_exp_f32_e32 v221, v127
	v_cvt_pk_bf16_f32 v184, v120, v121
	v_cvt_pk_bf16_f32 v185, v122, v123
	s_waitcnt lgkmcnt(0)
	s_barrier
	v_mfma_f32_32x32x16_bf16 v[48:63], v[176:179], v[112:115], v[48:63]
	ds_read_b128 v[68:71], v76 offset:49152
	ds_read_b128 v[72:75], v76 offset:57344
	ds_read_b64_tr_b16 v[120:121], v194 offset:0x3000
	ds_read_b64_tr_b16 v[122:123], v194 offset:0x3800
	ds_read_b64_tr_b16 v[124:125], v194 offset:0x3200
	ds_read_b64_tr_b16 v[126:127], v194 offset:0x3a00
	ds_read_b64_tr_b16 v[252:253], v194 offset:0x3400
	ds_read_b64_tr_b16 v[254:255], v194 offset:0x3c00
	ds_read_b64_tr_b16 v[216:217], v194 offset:0x3600
	ds_read_b64_tr_b16 v[218:219], v194 offset:0x3e00
	v_cvt_pk_bf16_f32 v186, v160, v161
	v_cvt_pk_bf16_f32 v187, v220, v221
	v_exp_f32_e32 v96, v96
	v_exp_f32_e32 v97, v97
	v_mfma_f32_32x32x16_bf16 v[32:47], v[176:179], v[116:119], v[32:47]
	v_exp_f32_e32 v98, v98
	v_exp_f32_e32 v99, v99
	s_waitcnt vmcnt(3)
	ds_write_b128 v188, v[156:159]
	global_load_dwordx4 v[156:159], v247, s[98:99] offset:2048
	v_mfma_f32_32x32x16_bf16 v[0:15], v[176:179], v[248:251], v[0:15]
	v_exp_f32_e32 v100, v100
	v_exp_f32_e32 v101, v101
	v_mfma_f32_32x32x16_bf16 v[16:31], v[176:179], v[212:215], v[16:31]
	v_cvt_pk_bf16_f32 v176, v96, v97
	v_cvt_pk_bf16_f32 v177, v98, v99
	v_exp_f32_e32 v96, v102
	v_exp_f32_e32 v97, v103
	s_waitcnt lgkmcnt(0)
	v_mfma_f32_32x32x16_bf16 v[48:63], v[172:175], v[120:123], v[48:63]
	v_cvt_pk_bf16_f32 v178, v100, v101
	v_cvt_pk_bf16_f32 v179, v96, v97
	v_exp_f32_e32 v98, v104
	v_exp_f32_e32 v99, v105
	v_mfma_f32_32x32x16_bf16 v[32:47], v[172:175], v[124:127], v[32:47]
	v_exp_f32_e32 v96, v106
	v_exp_f32_e32 v97, v107
	s_waitcnt vmcnt(3)
	ds_write_b128 v189, v[152:155]
	global_load_dwordx4 v[152:155], v247, s[100:101] offset:2048
	v_mfma_f32_32x32x16_bf16 v[0:15], v[172:175], v[252:255], v[0:15]
	v_exp_f32_e32 v100, v108
	v_exp_f32_e32 v101, v109
	v_mfma_f32_32x32x16_bf16 v[16:31], v[172:175], v[216:219], v[16:31]
	v_cvt_pk_bf16_f32 v172, v98, v99
	v_cvt_pk_bf16_f32 v173, v96, v97
	v_exp_f32_e32 v102, v110
	v_exp_f32_e32 v103, v111
	v_cvt_pk_bf16_f32 v174, v100, v101
	v_cvt_pk_bf16_f32 v175, v102, v103
	s_add_i32 s7, s7, 1
	s_mov_b32 s27, s6
	s_mov_b32 s6, s10
	s_cmp_lg_u32 s55, s7
	s_mov_b32 s10, s26
	s_cbranch_scc1 .LBB0_316
; #define MFMA32(a, b, c) __builtin_amdgcn_mfma_f32_32x32x16_bf16(a, b, c, 0, 0, 0)
; template <bool SAFE>
; __device__ __forceinline__ void diff_core(const bf16* __restrict__ Kh, const bf16* __restrict__ Vh, const int NT, const bf16x8* qr, char* lds,
;                                           const int wid, const int lane_unused, f32x16* o, f32x16& lacc, float& l_reg) {
;     ...
;   pv_d0(o, vb0 + bp * SHM_V, pa0, pa1, pa2, pa3);
;   if constexpr (!SAFE) {
;     lacc = MFMA32(pa0, ones, lacc); lacc = MFMA32(pa1, ones, lacc); lacc = MFMA32(pa2, ones, lacc); lacc = MFMA32(pa3, ones, lacc); }
; __device__ __forceinline__ void diff_attn_item(const bf16* __restrict__ qkv, bf16* __restrict__ mix, const float* __restrict__ dg,
;                                int tok0  , int key0  , int seq, int head, float lam, float oscale, const int W) {
;     ...
;     bool bad = (FORCE_SAFE != 0);
; #pragma unroll
;     for (int r = 0; r < 16; ++r) bad = bad || !(lacc[r] < 1.0e30f);
;     if (lane == 0) flag_l[wid] = __any(bad) ? 1 : 0;
	v_mov_b32_e32 v160, v180
	v_mov_b32_e32 v161, v181
	v_mov_b32_e32 v170, v184
	v_mov_b32_e32 v171, v185
	v_mov_b32_e32 v180, v176
	v_mov_b32_e32 v181, v177
	v_mov_b32_e32 v188, v172
	v_mov_b32_e32 v189, v173
	s_waitcnt vmcnt(0)
	v_add_u32_e32 v168, s11, v211
	ds_read_b64_tr_b16 v[80:81], v168 offset:0
	ds_read_b64_tr_b16 v[82:83], v168 offset:0x800
	ds_read_b64_tr_b16 v[84:85], v168 offset:0x1000
	ds_read_b64_tr_b16 v[86:87], v168 offset:0x1800
	ds_read_b64_tr_b16 v[88:89], v168 offset:0x2000
	ds_read_b64_tr_b16 v[90:91], v168 offset:0x2800
	ds_read_b64_tr_b16 v[92:93], v168 offset:0x3000
	ds_read_b64_tr_b16 v[94:95], v168 offset:0x3800
	s_waitcnt lgkmcnt(0)
	s_waitcnt vmcnt(0)
	v_mov_b32_e32 v162, v182
	v_mov_b32_e32 v163, v183
	v_mov_b32_e32 v172, v186
	v_mov_b32_e32 v173, v187
	v_mov_b32_e32 v182, v178
	v_mov_b32_e32 v183, v179
	v_mov_b32_e32 v190, v174
	v_mov_b32_e32 v191, v175
	ds_read_b64_tr_b16 v[96:97], v168 offset:0x200
	ds_read_b64_tr_b16 v[98:99], v168 offset:0xa00
	ds_read_b64_tr_b16 v[100:101], v168 offset:0x1200
	ds_read_b64_tr_b16 v[102:103], v168 offset:0x1a00
	ds_read_b64_tr_b16 v[104:105], v168 offset:0x2200
	ds_read_b64_tr_b16 v[106:107], v168 offset:0x2a00
	ds_read_b64_tr_b16 v[108:109], v168 offset:0x3200
	ds_read_b64_tr_b16 v[110:111], v168 offset:0x3a00
	s_waitcnt lgkmcnt(0)
	ds_read_b64_tr_b16 v[112:113], v168 offset:0x400
	ds_read_b64_tr_b16 v[114:115], v168 offset:0xc00
	ds_read_b64_tr_b16 v[116:117], v168 offset:0x1400
	ds_read_b64_tr_b16 v[118:119], v168 offset:0x1c00
	ds_read_b64_tr_b16 v[120:121], v168 offset:0x2400
	ds_read_b64_tr_b16 v[122:123], v168 offset:0x2c00
	ds_read_b64_tr_b16 v[124:125], v168 offset:0x3400
	ds_read_b64_tr_b16 v[126:127], v168 offset:0x3c00
	s_waitcnt lgkmcnt(0)
	ds_read_b64_tr_b16 v[152:153], v168 offset:0x600
	ds_read_b64_tr_b16 v[154:155], v168 offset:0xe00
	ds_read_b64_tr_b16 v[156:157], v168 offset:0x1600
	ds_read_b64_tr_b16 v[158:159], v168 offset:0x1e00
	ds_read_b64_tr_b16 v[164:165], v168 offset:0x2600
	ds_read_b64_tr_b16 v[166:167], v168 offset:0x2e00
	ds_read_b64_tr_b16 v[174:175], v168 offset:0x3600
	ds_read_b64_tr_b16 v[176:177], v168 offset:0x3e00
	s_waitcnt lgkmcnt(0)
	v_mfma_f32_16x16x32_bf16 v[64:67], v[160:163], v[148:151], v[64:67]
	v_cmp_eq_u32_e32 vcc, 0, v200
	v_mfma_f32_32x32x16_bf16 v[48:63], v[160:163], v[80:83], v[48:63]
	v_mfma_f32_32x32x16_bf16 v[32:47], v[160:163], v[96:99], v[32:47]
	v_mfma_f32_32x32x16_bf16 v[0:15], v[160:163], v[112:115], v[0:15]
	v_mfma_f32_32x32x16_bf16 v[16:31], v[160:163], v[152:155], v[16:31]
	v_mfma_f32_16x16x32_bf16 v[64:67], v[170:173], v[148:151], v[64:67]
	v_mfma_f32_32x32x16_bf16 v[48:63], v[170:173], v[84:87], v[48:63]
	v_mfma_f32_32x32x16_bf16 v[32:47], v[170:173], v[100:103], v[32:47]
	v_mfma_f32_32x32x16_bf16 v[0:15], v[170:173], v[116:119], v[0:15]
	v_mfma_f32_32x32x16_bf16 v[16:31], v[170:173], v[156:159], v[16:31]
	v_mfma_f32_16x16x32_bf16 v[64:67], v[180:183], v[148:151], v[64:67]
	v_mfma_f32_32x32x16_bf16 v[48:63], v[180:183], v[88:91], v[48:63]
	v_mfma_f32_32x32x16_bf16 v[32:47], v[180:183], v[104:107], v[32:47]
	v_mfma_f32_32x32x16_bf16 v[0:15], v[180:183], v[120:123], v[0:15]
	v_mfma_f32_32x32x16_bf16 v[16:31], v[180:183], v[164:167], v[16:31]
	v_mfma_f32_16x16x32_bf16 v[64:67], v[188:191], v[148:151], v[64:67]
	v_mfma_f32_32x32x16_bf16 v[48:63], v[188:191], v[92:95], v[48:63]
	v_mfma_f32_32x32x16_bf16 v[32:47], v[188:191], v[108:111], v[32:47]
	v_mfma_f32_32x32x16_bf16 v[0:15], v[188:191], v[124:127], v[0:15]
	v_mfma_f32_32x32x16_bf16 v[16:31], v[188:191], v[174:177], v[16:31]
	v_and_b32_e32 v248, 15, v200
	v_lshrrev_b32_e32 v249, 4, v200
	v_and_b32_e32 v250, 1, v200
	v_lshlrev_b32_e32 v249, 4, v249
	v_lshl_add_u32 v249, v250, 6, v249
	v_add_u32_e32 v249, s62, v249
	v_cmp_gt_u32_e64 s[98:99], 2, v248
	v_lshl_add_u32 v250, v198, 4, s62
	s_nop 7
	s_and_saveexec_b64 s[100:101], s[98:99]
	ds_write_b128 v249, v[64:67]
	s_mov_b64 exec, s[100:101]
	s_waitcnt lgkmcnt(0)
	ds_read_b128 v[64:67], v250
	ds_read_b128 v[68:71], v250 offset:32
	ds_read_b128 v[72:75], v250 offset:64
	ds_read_b128 v[76:79], v250 offset:96
	s_waitcnt lgkmcnt(0)
	s_and_saveexec_b64 s[10:11], vcc
	s_cbranch_execz .LBB0_319
	s_nop 5
	v_cmp_ngt_f32_e32 vcc, s44, v64
	v_cmp_ngt_f32_e64 s[6:7], s44, v65
	s_or_b64 s[6:7], vcc, s[6:7]
	v_cmp_ngt_f32_e32 vcc, s44, v66
	s_or_b64 s[6:7], s[6:7], vcc
	v_cmp_ngt_f32_e32 vcc, s44, v67
	s_or_b64 s[6:7], s[6:7], vcc
	v_cmp_ngt_f32_e32 vcc, s44, v68
	s_or_b64 s[6:7], s[6:7], vcc
	v_cmp_ngt_f32_e32 vcc, s44, v69
	s_or_b64 s[6:7], s[6:7], vcc
	v_cmp_ngt_f32_e32 vcc, s44, v70
	s_or_b64 s[6:7], s[6:7], vcc
	v_cmp_ngt_f32_e32 vcc, s44, v71
	s_or_b64 s[6:7], s[6:7], vcc
	v_cmp_ngt_f32_e32 vcc, s44, v72
	s_or_b64 s[6:7], s[6:7], vcc
	v_cmp_ngt_f32_e32 vcc, s44, v73
	s_or_b64 s[6:7], s[6:7], vcc
	v_cmp_ngt_f32_e32 vcc, s44, v74
	s_or_b64 s[6:7], s[6:7], vcc
	v_cmp_ngt_f32_e32 vcc, s44, v75
	s_or_b64 s[6:7], s[6:7], vcc
	v_cmp_ngt_f32_e32 vcc, s44, v76
	s_or_b64 s[6:7], s[6:7], vcc
	v_cmp_ngt_f32_e32 vcc, s44, v77
	s_or_b64 s[6:7], s[6:7], vcc
	v_cmp_ngt_f32_e32 vcc, s44, v78
	s_or_b64 s[6:7], s[6:7], vcc
	v_cmp_ngt_f32_e32 vcc, s44, v79
	s_or_b64 s[6:7], s[6:7], vcc
	v_cndmask_b32_e64 v80, 0, 1, s[6:7]
	v_cmp_ne_u32_e32 vcc, 0, v80
	s_cmp_lg_u64 vcc, 0
	s_cselect_b64 s[6:7], -1, 0
	v_cndmask_b32_e64 v80, 0, 1, s[6:7]
	v_readlane_b32 s6, v246, 17
	s_nop 1
	v_mov_b32_e32 v81, s6
	ds_write_b32 v81, v80
